# dif attention score-accumulator init with 64-bit moves, on top of the conv/combine/scan rewrites
# speedup vs baseline: 1.0003x; 1.0003x over previous
; #define LAS __attribute__((address_space(3)))
; __device__ __forceinline__ float shx(float v, int mask, int lane) { return __int_as_float(__builtin_amdgcn_ds_bpermute((lane ^ mask) << 2, __float_as_int(v))); }
; __device__ __forceinline__ void attn_dif_unit(LAS unsigned char* lds, const int tid, const int wave_s, const bf16_t* q, const bf16_t* k0, const bf16_t* k1, const bf16_t* vt0, const bf16_t* vt1, ...
;     ...
;             {
;                 bf16x8 qf[4], kfa[4], kfb[4];
; #pragma unroll
;                 for (int ks = 0; ks < 4; ++ks) qf[ks] = *(const LAS bf16x8*)(qb + c32 * DA_KP + m * 128 + ks * 32 + hi * 16);
; #pragma unroll
;                 for (int ks = 0; ks < 4; ++ks) kfa[ks] = *(const LAS bf16x8*)(kb + c32 * DA_KP + m * 128 + ks * 32 + hi * 16);
; #pragma unroll
;                 for (int ks = 0; ks < 4; ++ks) kfb[ks] = *(const LAS bf16x8*)(kb + (32 + c32) * DA_KP + m * 128 + ks * 32 + hi * 16);
; #pragma unroll
;                 for (int r = 0; r < 16; ++r) { sacc[0][r] = nm; sacc[1][r] = nm; }
; #pragma unroll
;                 for (int ks = 0; ks < 4; ++ks) sacc[0] = __builtin_amdgcn_mfma_f32_32x32x16_bf16(kfa[ks], qf[ks], sacc[0], 0, 0, 0);
; #pragma unroll
;                 for (int ks = 0; ks < 4; ++ks) sacc[1] = __builtin_amdgcn_mfma_f32_32x32x16_bf16(kfb[ks], qf[ks], sacc[1], 0, 0, 0);
;             }
;             float mx = fmaxf(sacc[0][0], sacc[1][0]);
; #pragma unroll
;             for (int a = 0; a < 2; ++a)
; #pragma unroll
;                 for (int r = 1; r < 16; r += 2) mx = fmaxf(fmaxf(mx, sacc[a][r]), sacc[a][r + 1 < 16 ? r + 1 : r]);
;             mx = fmaxf(mx, shx(mx, 32, lane));
.Ldif_noload:
.LBB0_989:
	v_mul_u32_u24_e32 v0, 0x110, v208
	v_add_u32_e32 v0, s22, v0
	v_add_u32_e32 v252, v0, v213
	ds_read_b128 v[2:5], v215
	ds_read_b128 v[6:9], v252
	v_xor_b32_e32 v144, 0x80000000, v218
	v_mov_b32_e32 v145, v144
	v_mov_b64_e32 v[146:147], v[144:145]
	v_mov_b64_e32 v[148:149], v[144:145]
	v_mov_b64_e32 v[150:151], v[144:145]
	v_mov_b64_e32 v[152:153], v[144:145]
	v_mov_b64_e32 v[154:155], v[144:145]
	v_mov_b64_e32 v[156:157], v[144:145]
	v_mov_b64_e32 v[158:159], v[144:145]
	s_cmp_eq_u32 s55, 1
	s_cselect_b64 s[6:7], -1, 0
	s_waitcnt lgkmcnt(0)
	v_mfma_f32_32x32x16_bf16 v[160:175], v[6:9], v[2:5], v[144:159]
	ds_read_b128 v[6:9], v252 offset:32
	ds_read_b128 v[10:13], v215 offset:32
	s_cmp_lg_u32 s55, 1
	s_cselect_b64 s[10:11], -1, 0
	s_and_b64 vcc, exec, s[10:11]
	s_waitcnt lgkmcnt(0)
	v_mfma_f32_32x32x16_bf16 v[160:175], v[6:9], v[10:13], v[160:175]
	ds_read_b128 v[6:9], v252 offset:64
	ds_read_b128 v[192:195], v215 offset:64
	s_waitcnt lgkmcnt(0)
	v_mfma_f32_32x32x16_bf16 v[160:175], v[6:9], v[192:195], v[160:175]
	ds_read_b128 v[6:9], v252 offset:8704
	s_waitcnt lgkmcnt(0)
	v_mfma_f32_32x32x16_bf16 v[144:159], v[6:9], v[2:5], v[144:159]
	ds_read_b128 v[2:5], v252 offset:8736
	s_waitcnt lgkmcnt(0)
	v_mfma_f32_32x32x16_bf16 v[144:159], v[2:5], v[10:13], v[144:159]
	ds_read_b128 v[2:5], v252 offset:8768
	s_waitcnt lgkmcnt(0)
	v_mfma_f32_32x32x16_bf16 v[144:159], v[2:5], v[192:195], v[144:159]
	ds_read_b128 v[2:5], v252 offset:8800
	ds_read_b128 v[6:9], v215 offset:96
	s_waitcnt lgkmcnt(0)
	v_mfma_f32_32x32x16_bf16 v[144:159], v[2:5], v[6:9], v[144:159]
	ds_read_b128 v[2:5], v252 offset:96
	s_waitcnt lgkmcnt(0)
	v_mfma_f32_32x32x16_bf16 v[160:175], v[2:5], v[6:9], v[160:175]
	s_nop 8
	v_max_f32_e32 v0, v144, v144
	s_nop 1
	v_max_f32_e32 v2, v160, v160
	v_max_f32_e32 v0, v2, v0
	v_max3_f32 v0, v0, v161, v162
	v_max3_f32 v0, v0, v163, v164
	v_max3_f32 v0, v0, v165, v166
	v_max3_f32 v0, v0, v167, v168
	v_max3_f32 v0, v0, v169, v170
	v_max3_f32 v0, v0, v171, v172
	v_max3_f32 v0, v0, v173, v174
	v_max3_f32 v0, v0, v175, v145
	v_max3_f32 v0, v0, v146, v147
	v_max3_f32 v0, v0, v148, v149
	v_max3_f32 v0, v0, v150, v151
	v_max3_f32 v0, v0, v152, v153
	v_max3_f32 v0, v0, v154, v155
	v_max3_f32 v0, v0, v156, v157
	v_max3_f32 v0, v0, v158, v159
	ds_bpermute_b32 v2, v203, v0
	s_waitcnt lgkmcnt(0)
	v_max_f32_e32 v2, v2, v2
	v_max_f32_e32 v192, v0, v2
	s_cbranch_vccz .LBB0_993
	v_cmp_lt_f32_e32 vcc, s64, v192
	s_mov_b64 s[14:15], 0
	s_mov_b64 s[12:13], 0
	s_cbranch_vccz .LBB0_992
	v_max_f32_e32 v0, v192, v192
	v_max_f32_e32 v0, 0, v0
	s_mov_b64 s[12:13], -1
